# P1 K-loop: LDS-DMA loads in saddr+voffset form, precomputed ds_read bases, scalar mask -- no VALU in the load segments
# baseline (speedup 1.0000x reference)
.LBB0_117:
	s_add_u32 s26, s38, 0x5000000
	s_addc_u32 s27, s39, 0
	s_add_u32 s28, s38, 0x8000000
	s_addc_u32 s29, s39, 0
	v_writelane_b32 v240, s28, 9
	v_lshl_add_u64 v[8:9], v[8:9], 0, s[58:59]
	s_waitcnt vmcnt(2)
	s_barrier
	v_writelane_b32 v240, s29, 10
	s_add_u32 s28, s38, 0xd000000
	s_addc_u32 s29, s39, 0
	s_add_u32 s66, s38, 0x2d00000
	s_addc_u32 s67, s39, 0
	s_and_b32 s16, s13, 3
	s_add_i32 m0, s97, 0x18000
	s_lshl_b32 s60, s30, 6
	s_lshl_b32 s30, s30, 13
	s_lshl_b32 s40, s16, 12
	global_load_lds_dwordx4 v[8:9], off
	v_lshl_add_u64 v[6:7], v[6:7], 0, s[58:59]
	s_add_i32 m0, s97, 0x1a000
	s_add_i32 s61, s97, 0x8000
	s_add_i32 s13, s97, 0xa000
	global_load_lds_dwordx4 v[6:7], off
	v_lshl_add_u64 v[2:3], v[2:3], 0, s[58:59]
	s_mov_b32 m0, s61
	s_add_u32 s38, s44, 0x40080
	global_load_lds_dwordx4 v[2:3], off
	v_lshl_add_u64 v[2:3], v[4:5], 0, s[58:59]
	s_mov_b32 m0, s13
	s_addc_u32 s39, s45, 0
	global_load_lds_dwordx4 v[2:3], off
	s_add_i32 m0, s97, 0x1c000
	v_lshl_add_u64 v[2:3], s[38:39], 0, v[208:209]
	global_load_lds_dwordx4 v[2:3], off
	v_lshl_add_u64 v[2:3], s[38:39], 0, v[212:213]
	s_add_i32 m0, s97, 0x1e000
	v_and_b32_e32 v232, 15, v0
	global_load_lds_dwordx4 v[2:3], off
	v_bfe_u32 v2, v0, 4, 2
	v_lshlrev_b32_e32 v3, 3, v2
	v_lshlrev_b32_e32 v4, 4, v2
	v_lshlrev_b32_e32 v5, 2, v0
	v_lshl_or_b32 v4, v232, 6, v4
	v_and_b32_e32 v5, 32, v5
	v_lshl_or_b32 v234, s16, 5, v3
	v_cmp_eq_u32_e64 s[38:39], 0, v2
	v_and_b32_e32 v2, 3, v0
	v_lshlrev_b32_e32 v3, 1, v0
	v_and_b32_e32 v0, 1, v0
	v_bitop3_b32 v233, v4, s40, v5 bitop3:0xde
	v_add_u32_e32 v244, 0x10000, v233
	v_add_u32_e32 v245, 0x14000, v233
	v_add_u32_e32 v246, 0x18000, v233
	v_add_u32_e32 v247, 0x1c000, v233
	v_cmp_eq_u32_e64 s[40:41], 0, v0
	v_lshlrev_b32_e32 v0, 14, v10
	v_and_b32_e32 v0, 0xffff8000, v0
	v_cmp_gt_u32_e64 s[42:43], 2, v2
	v_or_b32_e32 v236, v234, v2
	v_lshl_add_u32 v0, v11, 11, v0
	v_and_b32_e32 v2, 1, v10
	v_lshl_or_b32 v0, v2, 6, v0
	v_lshl_add_u32 v214, v12, 1, v0
	v_lshlrev_b32_e32 v0, 14, v13
	v_and_b32_e32 v0, 0xffff8000, v0
	s_waitcnt vmcnt(6)
	v_lshl_add_u32 v0, v14, 11, v0
	v_and_b32_e32 v2, 1, v13
	v_bitop3_b32 v6, v4, s30, v5 bitop3:0xde
	s_cmpk_lt_u32 s8, 0x100
	v_lshl_or_b32 v0, v2, 6, v0
	s_cselect_b64 s[68:69], -1, 0
	s_mov_b32 s8, 0
	v_and_b32_e32 v235, 24, v3
	v_mov_b32_e32 v215, v1
	v_lshl_add_u32 v216, v15, 1, v0
	v_mov_b32_e32 v217, v1
	v_add_u32_e32 v237, 0, v6
	s_barrier
	s_branch .LBB0_120

.LBB0_129:
	s_add_u32 s44, s80, 0xfffc0080
	s_addc_u32 s45, s81, -1
	s_add_i32 s88, 0, 0x10000
	s_cmp_eq_u32 s87, 12
	s_cselect_b32 s85, s30, s45
	s_cselect_b32 s84, s47, s44
	s_cselect_b32 s83, s49, s86
	s_cselect_b32 s82, s71, s73
	s_add_u32 s100, s84, 0x80
	s_addc_u32 s101, s85, 0
	s_add_i32 s89, 0, 0x14000
	ds_read_b128 v[148:151], v244
	ds_read_b128 v[152:155], v244 offset:1024
	ds_read_b128 v[156:159], v244 offset:2048
	ds_read_b128 v[160:163], v244 offset:3072
	s_waitcnt lgkmcnt(0)
	ds_read_b128 v[132:135], v245
	ds_read_b128 v[136:139], v245 offset:1024
	ds_read_b128 v[140:143], v245 offset:2048
	ds_read_b128 v[144:147], v245 offset:3072
	s_add_i32 m0, s97, 0xc000
	ds_read_b128 v[164:167], v237
	ds_read_b128 v[168:171], v237 offset:1024
	ds_read_b128 v[172:175], v237 offset:2048
	ds_read_b128 v[176:179], v237 offset:3072
	ds_read_b128 v[180:183], v237 offset:4096
	ds_read_b128 v[184:187], v237 offset:5120
	ds_read_b128 v[188:191], v237 offset:6144
	ds_read_b128 v[192:195], v237 offset:7168
	global_load_lds_dwordx4 v214, s[80:81]
	s_add_i32 m0, s97, 0xe000
	s_nop 0
	global_load_lds_dwordx4 v216, s[80:81]
	s_waitcnt vmcnt(8)
	s_waitcnt lgkmcnt(0)
	s_barrier
	s_setprio 1
	s_waitcnt lgkmcnt(0)
	v_mfma_f32_16x16x32_bf16 v[128:131], v[148:151], v[164:167], v[128:131]
	v_mfma_f32_16x16x32_bf16 v[120:123], v[156:159], v[164:167], v[120:123]
	v_mfma_f32_16x16x32_bf16 v[124:127], v[148:151], v[172:175], v[124:127]
	v_mfma_f32_16x16x32_bf16 v[116:119], v[156:159], v[172:175], v[116:119]
	v_mfma_f32_16x16x32_bf16 v[96:99], v[148:151], v[180:183], v[96:99]
	v_mfma_f32_16x16x32_bf16 v[88:91], v[156:159], v[180:183], v[88:91]
	v_mfma_f32_16x16x32_bf16 v[92:95], v[148:151], v[188:191], v[92:95]
	v_mfma_f32_16x16x32_bf16 v[84:87], v[156:159], v[188:191], v[84:87]
	v_mfma_f32_16x16x32_bf16 v[128:131], v[152:155], v[168:171], v[128:131]
	v_mfma_f32_16x16x32_bf16 v[120:123], v[160:163], v[168:171], v[120:123]
	v_mfma_f32_16x16x32_bf16 v[124:127], v[152:155], v[176:179], v[124:127]
	v_mfma_f32_16x16x32_bf16 v[116:119], v[160:163], v[176:179], v[116:119]
	v_mfma_f32_16x16x32_bf16 v[96:99], v[152:155], v[184:187], v[96:99]
	v_mfma_f32_16x16x32_bf16 v[88:91], v[160:163], v[184:187], v[88:91]
	v_mfma_f32_16x16x32_bf16 v[92:95], v[152:155], v[192:195], v[92:95]
	v_mfma_f32_16x16x32_bf16 v[84:87], v[160:163], v[192:195], v[84:87]
	v_mfma_f32_16x16x32_bf16 v[112:115], v[132:135], v[164:167], v[112:115]
	v_mfma_f32_16x16x32_bf16 v[104:107], v[140:143], v[164:167], v[104:107]
	v_mfma_f32_16x16x32_bf16 v[108:111], v[132:135], v[172:175], v[108:111]
	v_mfma_f32_16x16x32_bf16 v[100:103], v[140:143], v[172:175], v[100:103]
	v_mfma_f32_16x16x32_bf16 v[80:83], v[132:135], v[180:183], v[80:83]
	v_mfma_f32_16x16x32_bf16 v[72:75], v[140:143], v[180:183], v[72:75]
	v_mfma_f32_16x16x32_bf16 v[76:79], v[132:135], v[188:191], v[76:79]
	v_mfma_f32_16x16x32_bf16 v[68:71], v[140:143], v[188:191], v[68:71]
	v_mfma_f32_16x16x32_bf16 v[112:115], v[136:139], v[168:171], v[112:115]
	v_mfma_f32_16x16x32_bf16 v[104:107], v[144:147], v[168:171], v[104:107]
	v_mfma_f32_16x16x32_bf16 v[108:111], v[136:139], v[176:179], v[108:111]
	v_mfma_f32_16x16x32_bf16 v[100:103], v[144:147], v[176:179], v[100:103]
	v_mfma_f32_16x16x32_bf16 v[80:83], v[136:139], v[184:187], v[80:83]
	v_mfma_f32_16x16x32_bf16 v[72:75], v[144:147], v[184:187], v[72:75]
	v_mfma_f32_16x16x32_bf16 v[76:79], v[136:139], v[192:195], v[76:79]
	v_mfma_f32_16x16x32_bf16 v[68:71], v[144:147], v[192:195], v[68:71]
	s_setprio 0
	s_barrier
	s_add_i32 s44, s88, s96
	s_mov_b32 m0, s44
	ds_read_b128 v[188:191], v237 offset:16384
	ds_read_b128 v[192:195], v237 offset:17408
	ds_read_b128 v[180:183], v237 offset:18432
	ds_read_b128 v[184:187], v237 offset:19456
	ds_read_b128 v[172:175], v237 offset:20480
	ds_read_b128 v[176:179], v237 offset:21504
	ds_read_b128 v[164:167], v237 offset:22528
	ds_read_b128 v[168:171], v237 offset:23552
	global_load_lds_dwordx4 v208, s[82:83]
	s_add_i32 m0, s44, 0x2000
	s_add_u32 s44, s82, 0x40000
	s_addc_u32 s45, s83, 0
	s_add_i32 s88, s89, s96
	global_load_lds_dwordx4 v212, s[82:83]
	s_mov_b32 m0, s88
	s_nop 0
	global_load_lds_dwordx4 v208, s[44:45]
	s_add_i32 m0, s88, 0x2000
	s_nop 0
	global_load_lds_dwordx4 v212, s[44:45]
	s_mov_b32 m0, s97
	s_andn2_b64 s[98:99], exec, s[50:51]
	global_load_lds_dwordx4 v206, s[84:85]
	s_mov_b32 m0, s25
	s_andn2_b64 vcc, exec, s[50:51]
	global_load_lds_dwordx4 v210, s[84:85]
	s_waitcnt vmcnt(8)
	s_waitcnt lgkmcnt(0)
	s_barrier
	s_cbranch_vccnz .LBB0_131
	s_setprio 1
	s_waitcnt lgkmcnt(0)
	v_mfma_f32_16x16x32_bf16 v[64:67], v[148:151], v[188:191], v[64:67]
	v_mfma_f32_16x16x32_bf16 v[56:59], v[156:159], v[188:191], v[56:59]
	v_mfma_f32_16x16x32_bf16 v[60:63], v[148:151], v[180:183], v[60:63]
	v_mfma_f32_16x16x32_bf16 v[52:55], v[156:159], v[180:183], v[52:55]
	v_mfma_f32_16x16x32_bf16 v[32:35], v[148:151], v[172:175], v[32:35]
	v_mfma_f32_16x16x32_bf16 v[24:27], v[156:159], v[172:175], v[24:27]
	v_mfma_f32_16x16x32_bf16 v[28:31], v[148:151], v[164:167], v[28:31]
	v_mfma_f32_16x16x32_bf16 v[20:23], v[156:159], v[164:167], v[20:23]
	v_mfma_f32_16x16x32_bf16 v[64:67], v[152:155], v[192:195], v[64:67]
	v_mfma_f32_16x16x32_bf16 v[56:59], v[160:163], v[192:195], v[56:59]
	v_mfma_f32_16x16x32_bf16 v[60:63], v[152:155], v[184:187], v[60:63]
	v_mfma_f32_16x16x32_bf16 v[52:55], v[160:163], v[184:187], v[52:55]
	v_mfma_f32_16x16x32_bf16 v[32:35], v[152:155], v[176:179], v[32:35]
	v_mfma_f32_16x16x32_bf16 v[24:27], v[160:163], v[176:179], v[24:27]
	v_mfma_f32_16x16x32_bf16 v[28:31], v[152:155], v[168:171], v[28:31]
	v_mfma_f32_16x16x32_bf16 v[20:23], v[160:163], v[168:171], v[20:23]
	v_mfma_f32_16x16x32_bf16 v[48:51], v[132:135], v[188:191], v[48:51]
	v_mfma_f32_16x16x32_bf16 v[40:43], v[140:143], v[188:191], v[40:43]
	v_mfma_f32_16x16x32_bf16 v[44:47], v[132:135], v[180:183], v[44:47]
	v_mfma_f32_16x16x32_bf16 v[36:39], v[140:143], v[180:183], v[36:39]
	v_mfma_f32_16x16x32_bf16 v[16:19], v[132:135], v[172:175], v[16:19]
	v_mfma_f32_16x16x32_bf16 v[8:11], v[140:143], v[172:175], v[8:11]
	v_mfma_f32_16x16x32_bf16 v[12:15], v[132:135], v[164:167], v[12:15]
	v_mfma_f32_16x16x32_bf16 v[4:7], v[140:143], v[164:167], v[4:7]
	v_mfma_f32_16x16x32_bf16 v[48:51], v[136:139], v[192:195], v[48:51]
	v_mfma_f32_16x16x32_bf16 v[40:43], v[144:147], v[192:195], v[40:43]
	v_mfma_f32_16x16x32_bf16 v[44:47], v[136:139], v[184:187], v[44:47]
	v_mfma_f32_16x16x32_bf16 v[36:39], v[144:147], v[184:187], v[36:39]
	v_mfma_f32_16x16x32_bf16 v[16:19], v[136:139], v[176:179], v[16:19]
	v_mfma_f32_16x16x32_bf16 v[8:11], v[144:147], v[176:179], v[8:11]
	v_mfma_f32_16x16x32_bf16 v[12:15], v[136:139], v[168:171], v[12:15]
	v_mfma_f32_16x16x32_bf16 v[4:7], v[144:147], v[168:171], v[4:7]
	s_setprio 0
.LBB0_131:
	s_barrier
	s_add_i32 s88, 0, 0x18000
	s_add_i32 s89, 0, 0x1c000
	ds_read_b128 v[148:151], v246
	ds_read_b128 v[152:155], v246 offset:1024
	ds_read_b128 v[156:159], v246 offset:2048
	ds_read_b128 v[160:163], v246 offset:3072
	ds_read_b128 v[132:135], v247
	ds_read_b128 v[136:139], v247 offset:1024
	ds_read_b128 v[140:143], v247 offset:2048
	ds_read_b128 v[144:147], v247 offset:3072
	s_add_u32 s84, s84, 0x40000
	s_addc_u32 s85, s85, 0
	s_mov_b32 m0, s55
	s_waitcnt lgkmcnt(0)
	ds_read_b128 v[164:167], v237 offset:32768
	ds_read_b128 v[168:171], v237 offset:33792
	ds_read_b128 v[172:175], v237 offset:34816
	ds_read_b128 v[176:179], v237 offset:35840
	ds_read_b128 v[180:183], v237 offset:36864
	ds_read_b128 v[184:187], v237 offset:37888
	ds_read_b128 v[188:191], v237 offset:38912
	ds_read_b128 v[192:195], v237 offset:39936
	global_load_lds_dwordx4 v206, s[84:85]
	s_mov_b32 m0, s92
	s_nop 0
	global_load_lds_dwordx4 v210, s[84:85]
	s_waitcnt vmcnt(8)
	s_waitcnt lgkmcnt(0)
	s_barrier
	s_setprio 1
	s_waitcnt lgkmcnt(0)
	v_mfma_f32_16x16x32_bf16 v[128:131], v[148:151], v[164:167], v[128:131]
	v_mfma_f32_16x16x32_bf16 v[120:123], v[156:159], v[164:167], v[120:123]
	v_mfma_f32_16x16x32_bf16 v[124:127], v[148:151], v[172:175], v[124:127]
	v_mfma_f32_16x16x32_bf16 v[116:119], v[156:159], v[172:175], v[116:119]
	v_mfma_f32_16x16x32_bf16 v[96:99], v[148:151], v[180:183], v[96:99]
	v_mfma_f32_16x16x32_bf16 v[88:91], v[156:159], v[180:183], v[88:91]
	v_mfma_f32_16x16x32_bf16 v[92:95], v[148:151], v[188:191], v[92:95]
	v_mfma_f32_16x16x32_bf16 v[84:87], v[156:159], v[188:191], v[84:87]
	v_mfma_f32_16x16x32_bf16 v[128:131], v[152:155], v[168:171], v[128:131]
	v_mfma_f32_16x16x32_bf16 v[120:123], v[160:163], v[168:171], v[120:123]
	v_mfma_f32_16x16x32_bf16 v[124:127], v[152:155], v[176:179], v[124:127]
	v_mfma_f32_16x16x32_bf16 v[116:119], v[160:163], v[176:179], v[116:119]
	v_mfma_f32_16x16x32_bf16 v[96:99], v[152:155], v[184:187], v[96:99]
	v_mfma_f32_16x16x32_bf16 v[88:91], v[160:163], v[184:187], v[88:91]
	v_mfma_f32_16x16x32_bf16 v[92:95], v[152:155], v[192:195], v[92:95]
	v_mfma_f32_16x16x32_bf16 v[84:87], v[160:163], v[192:195], v[84:87]
	v_mfma_f32_16x16x32_bf16 v[112:115], v[132:135], v[164:167], v[112:115]
	v_mfma_f32_16x16x32_bf16 v[104:107], v[140:143], v[164:167], v[104:107]
	v_mfma_f32_16x16x32_bf16 v[108:111], v[132:135], v[172:175], v[108:111]
	v_mfma_f32_16x16x32_bf16 v[100:103], v[140:143], v[172:175], v[100:103]
	v_mfma_f32_16x16x32_bf16 v[80:83], v[132:135], v[180:183], v[80:83]
	v_mfma_f32_16x16x32_bf16 v[72:75], v[140:143], v[180:183], v[72:75]
	v_mfma_f32_16x16x32_bf16 v[76:79], v[132:135], v[188:191], v[76:79]
	v_mfma_f32_16x16x32_bf16 v[68:71], v[140:143], v[188:191], v[68:71]
	v_mfma_f32_16x16x32_bf16 v[112:115], v[136:139], v[168:171], v[112:115]
	v_mfma_f32_16x16x32_bf16 v[104:107], v[144:147], v[168:171], v[104:107]
	v_mfma_f32_16x16x32_bf16 v[108:111], v[136:139], v[176:179], v[108:111]
	v_mfma_f32_16x16x32_bf16 v[100:103], v[144:147], v[176:179], v[100:103]
	v_mfma_f32_16x16x32_bf16 v[80:83], v[136:139], v[184:187], v[80:83]
	v_mfma_f32_16x16x32_bf16 v[72:75], v[144:147], v[184:187], v[72:75]
	v_mfma_f32_16x16x32_bf16 v[76:79], v[136:139], v[192:195], v[76:79]
	v_mfma_f32_16x16x32_bf16 v[68:71], v[144:147], v[192:195], v[68:71]
	s_setprio 0
	s_barrier
	s_add_i32 s84, s88, s96
	s_and_b64 vcc, exec, s[98:99]
	s_add_u32 s44, s82, 0x80
	s_addc_u32 s45, s83, 0
	s_mov_b32 m0, s84
	ds_read_b128 v[188:191], v237 offset:49152
	ds_read_b128 v[192:195], v237 offset:50176
	ds_read_b128 v[180:183], v237 offset:51200
	ds_read_b128 v[184:187], v237 offset:52224
	ds_read_b128 v[172:175], v237 offset:53248
	ds_read_b128 v[176:179], v237 offset:54272
	ds_read_b128 v[164:167], v237 offset:55296
	ds_read_b128 v[168:171], v237 offset:56320
	global_load_lds_dwordx4 v208, s[44:45]
	s_add_i32 m0, s84, 0x2000
	s_add_i32 s84, s89, s96
	global_load_lds_dwordx4 v212, s[44:45]
	s_add_u32 s82, s82, 0x40080
	s_addc_u32 s83, s83, 0
	s_mov_b32 m0, s84
	s_nop 0
	global_load_lds_dwordx4 v208, s[82:83]
	s_add_i32 m0, s84, 0x2000
	s_nop 0
	global_load_lds_dwordx4 v212, s[82:83]
	s_mov_b32 m0, s61
	s_nop 0
	global_load_lds_dwordx4 v206, s[100:101]
	s_mov_b32 m0, s13
	s_nop 0
	global_load_lds_dwordx4 v210, s[100:101]
	s_mov_b64 s[44:45], s[98:99]
	s_waitcnt vmcnt(8)
	s_waitcnt lgkmcnt(0)
	s_barrier
	s_cbranch_vccnz .LBB0_128
	s_setprio 1
	s_waitcnt lgkmcnt(0)
	v_mfma_f32_16x16x32_bf16 v[64:67], v[148:151], v[188:191], v[64:67]
	v_mfma_f32_16x16x32_bf16 v[56:59], v[156:159], v[188:191], v[56:59]
	v_mfma_f32_16x16x32_bf16 v[60:63], v[148:151], v[180:183], v[60:63]
	v_mfma_f32_16x16x32_bf16 v[52:55], v[156:159], v[180:183], v[52:55]
	v_mfma_f32_16x16x32_bf16 v[32:35], v[148:151], v[172:175], v[32:35]
	v_mfma_f32_16x16x32_bf16 v[24:27], v[156:159], v[172:175], v[24:27]
	v_mfma_f32_16x16x32_bf16 v[28:31], v[148:151], v[164:167], v[28:31]
	v_mfma_f32_16x16x32_bf16 v[20:23], v[156:159], v[164:167], v[20:23]
	v_mfma_f32_16x16x32_bf16 v[64:67], v[152:155], v[192:195], v[64:67]
	v_mfma_f32_16x16x32_bf16 v[56:59], v[160:163], v[192:195], v[56:59]
	v_mfma_f32_16x16x32_bf16 v[60:63], v[152:155], v[184:187], v[60:63]
	v_mfma_f32_16x16x32_bf16 v[52:55], v[160:163], v[184:187], v[52:55]
	v_mfma_f32_16x16x32_bf16 v[32:35], v[152:155], v[176:179], v[32:35]
	v_mfma_f32_16x16x32_bf16 v[24:27], v[160:163], v[176:179], v[24:27]
	v_mfma_f32_16x16x32_bf16 v[28:31], v[152:155], v[168:171], v[28:31]
	v_mfma_f32_16x16x32_bf16 v[20:23], v[160:163], v[168:171], v[20:23]
	v_mfma_f32_16x16x32_bf16 v[48:51], v[132:135], v[188:191], v[48:51]
	v_mfma_f32_16x16x32_bf16 v[40:43], v[140:143], v[188:191], v[40:43]
	v_mfma_f32_16x16x32_bf16 v[44:47], v[132:135], v[180:183], v[44:47]
	v_mfma_f32_16x16x32_bf16 v[36:39], v[140:143], v[180:183], v[36:39]
	v_mfma_f32_16x16x32_bf16 v[16:19], v[132:135], v[172:175], v[16:19]
	v_mfma_f32_16x16x32_bf16 v[8:11], v[140:143], v[172:175], v[8:11]
	v_mfma_f32_16x16x32_bf16 v[12:15], v[132:135], v[164:167], v[12:15]
	v_mfma_f32_16x16x32_bf16 v[2:5], v[140:143], v[164:167], v[4:7]
	v_mfma_f32_16x16x32_bf16 v[48:51], v[136:139], v[192:195], v[48:51]
	v_mfma_f32_16x16x32_bf16 v[40:43], v[144:147], v[192:195], v[40:43]
	v_mfma_f32_16x16x32_bf16 v[44:47], v[136:139], v[184:187], v[44:47]
	v_mfma_f32_16x16x32_bf16 v[36:39], v[144:147], v[184:187], v[36:39]
	v_mfma_f32_16x16x32_bf16 v[16:19], v[136:139], v[176:179], v[16:19]
	v_mfma_f32_16x16x32_bf16 v[8:11], v[144:147], v[176:179], v[8:11]
	v_mfma_f32_16x16x32_bf16 v[12:15], v[136:139], v[168:171], v[12:15]
	v_mfma_f32_16x16x32_bf16 v[4:7], v[144:147], v[168:171], v[2:5]
	s_setprio 0
	s_branch .LBB0_128

	.amdhsa_kernel _Z10hybrid_fwd4Args
		.amdhsa_group_segment_fixed_size 0
		.amdhsa_private_segment_fixed_size 0
		.amdhsa_kernarg_size 440
		.amdhsa_user_sgpr_count 2
		.amdhsa_user_sgpr_dispatch_ptr 0
		.amdhsa_user_sgpr_queue_ptr 0
		.amdhsa_user_sgpr_kernarg_segment_ptr 1
		.amdhsa_user_sgpr_dispatch_id 0
		.amdhsa_user_sgpr_kernarg_preload_length 0
		.amdhsa_user_sgpr_kernarg_preload_offset 0
		.amdhsa_user_sgpr_private_segment_size 0
		.amdhsa_uses_dynamic_stack 0
		.amdhsa_enable_private_segment 0
		.amdhsa_system_sgpr_workgroup_id_x 1
		.amdhsa_system_sgpr_workgroup_id_y 0
		.amdhsa_system_sgpr_workgroup_id_z 0
		.amdhsa_system_sgpr_workgroup_info 0
		.amdhsa_system_vgpr_workitem_id 2
		.amdhsa_next_free_vgpr 248
		.amdhsa_next_free_sgpr 102
		.amdhsa_accum_offset 248
		.amdhsa_reserve_vcc 1
		.amdhsa_float_round_mode_32 0
		.amdhsa_float_round_mode_16_64 0
		.amdhsa_float_denorm_mode_32 3
		.amdhsa_float_denorm_mode_16_64 3
		.amdhsa_dx10_clamp 1
		.amdhsa_ieee_mode 1
		.amdhsa_fp16_overflow 0
		.amdhsa_tg_split 0
		.amdhsa_exception_fp_ieee_invalid_op 0
		.amdhsa_exception_fp_denorm_src 0
		.amdhsa_exception_fp_ieee_div_zero 0
		.amdhsa_exception_fp_ieee_overflow 0
		.amdhsa_exception_fp_ieee_underflow 0
		.amdhsa_exception_fp_ieee_inexact 0
		.amdhsa_exception_int_div_zero 0
	.end_amdhsa_kernel

.Lfunc_end0:
	.size	_Z10hybrid_fwd4Args, .Lfunc_end0-_Z10hybrid_fwd4Args
	.set _Z10hybrid_fwd4Args.num_vgpr, 248
	.set _Z10hybrid_fwd4Args.num_agpr, 0
	.set _Z10hybrid_fwd4Args.numbered_sgpr, 98
	.set _Z10hybrid_fwd4Args.num_named_barrier, 0
	.set _Z10hybrid_fwd4Args.private_seg_size, 0
	.set _Z10hybrid_fwd4Args.uses_vcc, 1
	.set _Z10hybrid_fwd4Args.uses_flat_scratch, 0
	.set _Z10hybrid_fwd4Args.has_dyn_sized_stack, 0
	.set _Z10hybrid_fwd4Args.has_recursion, 0
	.set _Z10hybrid_fwd4Args.has_indirect_call, 0

amdhsa.kernels:
  - .agpr_count:     0
    .args:
      - .offset:         0
        .size:           184
        .value_kind:     by_value
      - .offset:         184
        .size:           4
        .value_kind:     hidden_block_count_x
      - .offset:         188
        .size:           4
        .value_kind:     hidden_block_count_y
      - .offset:         192
        .size:           4
        .value_kind:     hidden_block_count_z
      - .offset:         196
        .size:           2
        .value_kind:     hidden_group_size_x
      - .offset:         198
        .size:           2
        .value_kind:     hidden_group_size_y
      - .offset:         200
        .size:           2
        .value_kind:     hidden_group_size_z
      - .offset:         202
        .size:           2
        .value_kind:     hidden_remainder_x
      - .offset:         204
        .size:           2
        .value_kind:     hidden_remainder_y
      - .offset:         206
        .size:           2
        .value_kind:     hidden_remainder_z
      - .offset:         224
        .size:           8
        .value_kind:     hidden_global_offset_x
      - .offset:         232
        .size:           8
        .value_kind:     hidden_global_offset_y
      - .offset:         240
        .size:           8
        .value_kind:     hidden_global_offset_z
      - .offset:         248
        .size:           2
        .value_kind:     hidden_grid_dims
      - .offset:         272
        .size:           8
        .value_kind:     hidden_multigrid_sync_arg
      - .offset:         304
        .size:           4
        .value_kind:     hidden_dynamic_lds_size
    .group_segment_fixed_size: 0
    .kernarg_segment_align: 8
    .kernarg_segment_size: 440
    .language:       OpenCL C
    .language_version:
      - 2
      - 0
    .max_flat_workgroup_size: 512
    .name:           _Z10hybrid_fwd4Args
    .private_segment_fixed_size: 0
    .sgpr_count:     108
    .sgpr_spill_count: 139
    .symbol:         _Z10hybrid_fwd4Args.kd
    .uniform_work_group_size: 1
    .uses_dynamic_stack: false
    .vgpr_count:     248
    .vgpr_spill_count: 0
    .wavefront_size: 64
